# GEMM1 gate epilogue prefetch deepened to 9 blocks (uses dead B-fragment registers)
# baseline (speedup 1.0000x reference)
; __device__ __forceinline__ unsigned cvt_pk_bf16(float lo, float hi) { unsigned r; asm volatile("v_cvt_pk_bf16_f32 %0, %1, %2" : "=v"(r) : "v"(lo), "v"(hi)); return r; }
; __device__ __forceinline__ float bflo(unsigned u) { return __uint_as_float(u << 16); }
; __device__ __forceinline__ float bfhi(unsigned u) { return __uint_as_float(u & 0xffff0000u); }
; __device__ __forceinline__ float sigm(float v) { return __builtin_amdgcn_rcpf(1.0f + __expf(-v)); }
; DI float bflo(unsigned u) { return __uint_as_float(u << 16); }
; DI float bfhi(unsigned u) { return __uint_as_float(u & 0xffff0000u); }
;     __device__ __forceinline__ void operator()(const f32x4 (&acc)[2][2][4][2], const Unit& u, int wr, int wc, int fr, int fq) const {
;         const int row0 = u.pm * BM + wr * 64 + fr; const int colt = u.pn * BM; const int t = colt / 512;
;         const bf16_t* gbase = G0 + (size_t)t * split_stride; const int col0 = colt + wc * 32 + 8 * fq, gcol0 = col0 - t * 512;
; #pragma unroll
;         for (int bj = 0; bj < 2; ++bj) {
;             const f32x4 b0 = *(const f32x4*)(gb + col0 + bj * HALF), b1 = *(const f32x4*)(gb + col0 + bj * HALF + 4);
; #pragma unroll
;             for (int ai = 0; ai < 2; ++ai)
; #pragma unroll
;                 for (int m = 0; m < 4; ++m) { const size_t row = (size_t)(row0 + ai * HALF + m * 16);
;                     const u32x4 g = *(const u32x4*)(gbase + row * 512 + gcol0 + bj * HALF);
;                     const f32x4 v0 = acc[ai][bj][m][0], v1 = acc[ai][bj][m][1];
;                     float r0 = v0[0] * sigm(bflo(g.x) + b0[0]), r1 = v0[1] * sigm(bfhi(g.x) + b0[1]), r2 = v0[2] * sigm(bflo(g.y) + b0[2]), r3 = v0[3] * sigm(bfhi(g.y) + b0[3]);
;                     float r4 = v1[0] * sigm(bflo(g.z) + b1[0]), r5 = v1[1] * sigm(bfhi(g.z) + b1[1]), r6 = v1[2] * sigm(bflo(g.w) + b1[2]), r7 = v1[3] * sigm(bfhi(g.w) + b1[3]);
;                     bf16_t* op = Mo + row * 1024 + col0 + bj * HALF;
;                     if (accum) { const u32x4 p = *(const u32x4*)op; r0 += bflo(p.x); r1 += bfhi(p.x); r2 += bflo(p.y); r3 += bfhi(p.y); r4 += bflo(p.z); r5 += bfhi(p.z); r6 += bflo(p.w); r7 += bfhi(p.w); }
;                     u32x4 w; w.x = cvt_pk_bf16(r0, r1); w.y = cvt_pk_bf16(r2, r3); w.z = cvt_pk_bf16(r4, r5); w.w = cvt_pk_bf16(r6, r7);
;                     *(u32x4*)op = w; }
.LBB0_880:
	s_lshr_b32 s2, s44, 31
	s_add_i32 s2, s44, s2
	s_ashr_i32 s24, s2, 1
	s_ashr_i32 s25, s24, 31
	s_lshl_b64 s[26:27], s[24:25], 24
	s_add_u32 s26, s36, s26
	s_addc_u32 s27, s37, s27
	v_lshl_or_b32 v154, s44, 8, v172
	s_lshl_b32 s2, s24, 9
	v_lshl_add_u32 v168, s22, 8, v1
	v_subrev_u32_e32 v114, s2, v154
	v_ashrrev_i32_e32 v115, 31, v114
	v_ashrrev_i32_e32 v169, 31, v168
	v_lshl_add_u64 v[170:171], v[114:115], 1, s[26:27]
	v_lshlrev_b64 v[114:115], 10, v[168:169]
	v_lshl_add_u64 v[158:159], v[170:171], 0, v[114:115]
	v_ashrrev_i32_e32 v155, 31, v154
	global_load_dwordx4 v[176:179], v[158:159], off
	v_lshl_add_u64 v[160:161], v[154:155], 2, s[78:79]
	global_load_dwordx4 v[118:121], v[160:161], off
	global_load_dwordx4 v[114:117], v[160:161], off offset:16
	v_lshlrev_b64 v[156:157], 11, v[168:169]
	v_or_b32_e32 v180, 16, v168
	v_lshlrev_b64 v[166:167], 1, v[154:155]
	v_ashrrev_i32_e32 v181, 31, v180
	v_lshl_add_u64 v[154:155], s[10:11], 0, v[156:157]
	v_lshlrev_b64 v[156:157], 10, v[180:181]
	v_lshl_add_u64 v[154:155], v[154:155], 0, v[166:167]
	v_lshl_add_u64 v[156:157], v[170:171], 0, v[156:157]
	s_andn2_b64 vcc, exec, s[6:7]
	s_mov_b64 s[6:7], -1
	v_mov_b32_e32 v250, v158
	v_mov_b32_e32 v251, v159
	s_mov_b64 s[98:99], 0x4000
	v_lshl_add_u64 v[248:249], v[250:251], 0, s[98:99]
	global_load_dwordx4 v[204:207], v[248:249], off
	s_mov_b64 s[98:99], 0x8000
	v_lshl_add_u64 v[248:249], v[250:251], 0, s[98:99]
	global_load_dwordx4 v[208:211], v[248:249], off
	s_mov_b64 s[98:99], 0xc000
	v_lshl_add_u64 v[248:249], v[250:251], 0, s[98:99]
	global_load_dwordx4 v[212:215], v[248:249], off
	s_mov_b64 s[98:99], 0x20000
	v_lshl_add_u64 v[248:249], v[250:251], 0, s[98:99]
	global_load_dwordx4 v[216:219], v[248:249], off
	s_mov_b64 s[98:99], 0x24000
	v_lshl_add_u64 v[248:249], v[250:251], 0, s[98:99]
	global_load_dwordx4 v[220:223], v[248:249], off
	s_mov_b64 s[98:99], 0x28000
	v_lshl_add_u64 v[248:249], v[250:251], 0, s[98:99]
	global_load_dwordx4 v[224:227], v[248:249], off
	s_mov_b64 s[98:99], 0x2c000
	v_lshl_add_u64 v[248:249], v[250:251], 0, s[98:99]
	global_load_dwordx4 v[188:191], v[248:249], off
	global_load_dwordx4 v[192:195], v[250:251], off offset:256
	s_mov_b64 s[98:99], 0x4000
	v_lshl_add_u64 v[248:249], v[250:251], 0, s[98:99]
	global_load_dwordx4 v[252:255], v[248:249], off offset:256
	global_load_dwordx4 v[240:243], v[160:161], off offset:512
	global_load_dwordx4 v[244:247], v[160:161], off offset:528
	s_waitcnt vmcnt(11)
	v_lshlrev_b32_e32 v184, 16, v179
	v_and_b32_e32 v179, 0xffff0000, v179
	v_lshlrev_b32_e32 v169, 16, v176
	v_and_b32_e32 v176, 0xffff0000, v176
	v_lshlrev_b32_e32 v182, 16, v177
	v_and_b32_e32 v177, 0xffff0000, v177
	v_lshlrev_b32_e32 v183, 16, v178
	v_and_b32_e32 v178, 0xffff0000, v178
	v_add_f32_e32 v179, v117, v179
	v_add_f32_e32 v169, v118, v169
	v_add_f32_e32 v176, v119, v176
	v_add_f32_e32 v182, v120, v182
	v_add_f32_e32 v177, v121, v177
	v_add_f32_e32 v183, v114, v183
	v_add_f32_e32 v178, v115, v178
	v_add_f32_e32 v184, v116, v184
	v_mul_f32_e32 v179, 0xbfb8aa3b, v179
	v_mul_f32_e32 v169, 0xbfb8aa3b, v169
	v_mul_f32_e32 v176, 0xbfb8aa3b, v176
	v_mul_f32_e32 v182, 0xbfb8aa3b, v182
	v_mul_f32_e32 v177, 0xbfb8aa3b, v177
	v_mul_f32_e32 v183, 0xbfb8aa3b, v183
	v_mul_f32_e32 v178, 0xbfb8aa3b, v178
	v_mul_f32_e32 v184, 0xbfb8aa3b, v184
	v_exp_f32_e32 v179, v179
	v_exp_f32_e32 v169, v169
	v_exp_f32_e32 v176, v176
	v_exp_f32_e32 v182, v182
	v_exp_f32_e32 v177, v177
	v_exp_f32_e32 v183, v183
	v_exp_f32_e32 v178, v178
	v_exp_f32_e32 v184, v184
	v_add_f32_e32 v179, 1.0, v179
	v_add_f32_e32 v169, 1.0, v169
	v_add_f32_e32 v176, 1.0, v176
	v_add_f32_e32 v182, 1.0, v182
	v_add_f32_e32 v177, 1.0, v177
	v_add_f32_e32 v183, 1.0, v183
	v_add_f32_e32 v178, 1.0, v178
	v_add_f32_e32 v184, 1.0, v184
	v_rcp_f32_e32 v179, v179
	v_rcp_f32_e32 v169, v169
	v_rcp_f32_e32 v176, v176
	v_rcp_f32_e32 v182, v182
	v_rcp_f32_e32 v177, v177
	v_rcp_f32_e32 v183, v183
	v_rcp_f32_e32 v178, v178
	v_rcp_f32_e32 v184, v184
	v_mul_f32_e32 v133, v133, v179
	v_mul_f32_e32 v134, v134, v169
	v_mul_f32_e32 v135, v135, v176
	v_mul_f32_e32 v136, v136, v182
	v_mul_f32_e32 v137, v137, v177
	v_mul_f32_e32 v169, v130, v183
	v_mul_f32_e32 v176, v131, v178
	v_mul_f32_e32 v177, v132, v184
	v_cvt_pk_bf16_f32 v130, v134, v135
	v_cvt_pk_bf16_f32 v131, v136, v137
	v_cvt_pk_bf16_f32 v132, v169, v176
	v_cvt_pk_bf16_f32 v133, v177, v133
	global_store_dwordx4 v[154:155], v[130:133], off
	s_nop 0
	v_or_b32_e32 v176, 32, v168
	v_lshlrev_b64 v[130:131], 11, v[180:181]
	v_ashrrev_i32_e32 v177, 31, v176
	v_lshl_add_u64 v[130:131], s[10:11], 0, v[130:131]
	v_lshlrev_b64 v[132:133], 10, v[176:177]
	v_lshl_add_u64 v[130:131], v[130:131], 0, v[166:167]
	v_lshl_add_u64 v[132:133], v[170:171], 0, v[132:133]
	s_waitcnt vmcnt(11)
; __device__ __forceinline__ unsigned cvt_pk_bf16(float lo, float hi) { unsigned r; asm volatile("v_cvt_pk_bf16_f32 %0, %1, %2" : "=v"(r) : "v"(lo), "v"(hi)); return r; }
; __device__ __forceinline__ float bflo(unsigned u) { return __uint_as_float(u << 16); }
; __device__ __forceinline__ float bfhi(unsigned u) { return __uint_as_float(u & 0xffff0000u); }
; __device__ __forceinline__ float sigm(float v) { return __builtin_amdgcn_rcpf(1.0f + __expf(-v)); }
; DI float bflo(unsigned u) { return __uint_as_float(u << 16); }
; DI float bfhi(unsigned u) { return __uint_as_float(u & 0xffff0000u); }
;     __device__ __forceinline__ void operator()(const f32x4 (&acc)[2][2][4][2], const Unit& u, int wr, int wc, int fr, int fq) const {
;     ...
;         for (int bj = 0; bj < 2; ++bj) {
;             const f32x4 b0 = *(const f32x4*)(gb + col0 + bj * HALF), b1 = *(const f32x4*)(gb + col0 + bj * HALF + 4);
; #pragma unroll
;             for (int ai = 0; ai < 2; ++ai)
; #pragma unroll
;                 for (int m = 0; m < 4; ++m) { const size_t row = (size_t)(row0 + ai * HALF + m * 16);
;                     const u32x4 g = *(const u32x4*)(gbase + row * 512 + gcol0 + bj * HALF);
;                     const f32x4 v0 = acc[ai][bj][m][0], v1 = acc[ai][bj][m][1];
;                     float r0 = v0[0] * sigm(bflo(g.x) + b0[0]), r1 = v0[1] * sigm(bfhi(g.x) + b0[1]), r2 = v0[2] * sigm(bflo(g.y) + b0[2]), r3 = v0[3] * sigm(bfhi(g.y) + b0[3]);
;                     float r4 = v1[0] * sigm(bflo(g.z) + b1[0]), r5 = v1[1] * sigm(bfhi(g.z) + b1[1]), r6 = v1[2] * sigm(bflo(g.w) + b1[2]), r7 = v1[3] * sigm(bfhi(g.w) + b1[3]);
;                     bf16_t* op = Mo + row * 1024 + col0 + bj * HALF;
;                     if (accum) { const u32x4 p = *(const u32x4*)op; r0 += bflo(p.x); r1 += bfhi(p.x); r2 += bflo(p.y); r3 += bfhi(p.y); r4 += bflo(p.z); r5 += bfhi(p.z); r6 += bflo(p.w); r7 += bfhi(p.w); }
;                     u32x4 w; w.x = cvt_pk_bf16(r0, r1); w.y = cvt_pk_bf16(r2, r3); w.z = cvt_pk_bf16(r4, r5); w.w = cvt_pk_bf16(r6, r7);
;                     *(u32x4*)op = w; }
	v_lshlrev_b32_e32 v180, 16, v207
	v_and_b32_e32 v137, 0xffff0000, v207
	v_lshlrev_b32_e32 v169, 16, v204
	v_and_b32_e32 v134, 0xffff0000, v204
	v_lshlrev_b32_e32 v178, 16, v205
	v_and_b32_e32 v135, 0xffff0000, v205
	v_lshlrev_b32_e32 v179, 16, v206
	v_and_b32_e32 v136, 0xffff0000, v206
	s_mov_b64 s[98:99], 0x8000
	v_lshl_add_u64 v[248:249], v[250:251], 0, s[98:99]
	global_load_dwordx4 v[204:207], v[248:249], off offset:256
	v_add_f32_e32 v137, v117, v137
	v_add_f32_e32 v169, v118, v169
	v_add_f32_e32 v134, v119, v134
	v_add_f32_e32 v178, v120, v178
	v_add_f32_e32 v135, v121, v135
	v_add_f32_e32 v179, v114, v179
	v_add_f32_e32 v136, v115, v136
	v_add_f32_e32 v180, v116, v180
	v_mul_f32_e32 v137, 0xbfb8aa3b, v137
	v_mul_f32_e32 v169, 0xbfb8aa3b, v169
	v_mul_f32_e32 v134, 0xbfb8aa3b, v134
	v_mul_f32_e32 v178, 0xbfb8aa3b, v178
	v_mul_f32_e32 v135, 0xbfb8aa3b, v135
	v_mul_f32_e32 v179, 0xbfb8aa3b, v179
	v_mul_f32_e32 v136, 0xbfb8aa3b, v136
	v_mul_f32_e32 v180, 0xbfb8aa3b, v180
	v_exp_f32_e32 v137, v137
	v_exp_f32_e32 v169, v169
	v_exp_f32_e32 v134, v134
	v_exp_f32_e32 v178, v178
	v_exp_f32_e32 v135, v135
	v_exp_f32_e32 v179, v179
	v_exp_f32_e32 v136, v136
	v_exp_f32_e32 v180, v180
	v_add_f32_e32 v137, 1.0, v137
	v_add_f32_e32 v169, 1.0, v169
	v_add_f32_e32 v134, 1.0, v134
	v_add_f32_e32 v178, 1.0, v178
	v_add_f32_e32 v135, 1.0, v135
	v_add_f32_e32 v179, 1.0, v179
	v_add_f32_e32 v136, 1.0, v136
	v_add_f32_e32 v180, 1.0, v180
	v_rcp_f32_e32 v137, v137
	v_rcp_f32_e32 v169, v169
	v_rcp_f32_e32 v134, v134
	v_rcp_f32_e32 v178, v178
	v_rcp_f32_e32 v135, v135
	v_rcp_f32_e32 v179, v179
	v_rcp_f32_e32 v136, v136
	v_rcp_f32_e32 v180, v180
	v_mul_f32_e32 v125, v125, v137
	v_mul_f32_e32 v126, v126, v169
	v_mul_f32_e32 v127, v127, v134
	v_mul_f32_e32 v128, v128, v178
	v_mul_f32_e32 v129, v129, v135
	v_mul_f32_e32 v134, v122, v179
	v_mul_f32_e32 v135, v123, v136
	v_mul_f32_e32 v136, v124, v180
	v_cvt_pk_bf16_f32 v122, v126, v127
	v_cvt_pk_bf16_f32 v123, v128, v129
	v_cvt_pk_bf16_f32 v124, v134, v135
	v_cvt_pk_bf16_f32 v125, v136, v125
	global_store_dwordx4 v[130:131], v[122:125], off
	s_nop 0
	v_or_b32_e32 v134, 48, v168
	v_lshlrev_b64 v[122:123], 11, v[176:177]
	v_ashrrev_i32_e32 v135, 31, v134
	v_lshl_add_u64 v[122:123], s[10:11], 0, v[122:123]
	v_lshlrev_b64 v[124:125], 10, v[134:135]
	v_lshl_add_u64 v[122:123], v[122:123], 0, v[166:167]
	v_lshl_add_u64 v[124:125], v[170:171], 0, v[124:125]
	s_waitcnt vmcnt(12)
	v_lshlrev_b32_e32 v176, 16, v211
	v_and_b32_e32 v129, 0xffff0000, v211
	v_lshlrev_b32_e32 v136, 16, v208
	v_and_b32_e32 v126, 0xffff0000, v208
	v_lshlrev_b32_e32 v137, 16, v209
	v_and_b32_e32 v127, 0xffff0000, v209
	v_lshlrev_b32_e32 v169, 16, v210
	v_and_b32_e32 v128, 0xffff0000, v210
	s_mov_b64 s[98:99], 0xc000
	v_lshl_add_u64 v[248:249], v[250:251], 0, s[98:99]
	global_load_dwordx4 v[208:211], v[248:249], off offset:256
	v_add_f32_e32 v129, v117, v129
	v_add_f32_e32 v136, v118, v136
	v_add_f32_e32 v126, v119, v126
	v_add_f32_e32 v137, v120, v137
	v_add_f32_e32 v127, v121, v127
	v_add_f32_e32 v169, v114, v169
	v_add_f32_e32 v128, v115, v128
	v_add_f32_e32 v176, v116, v176
	v_mul_f32_e32 v129, 0xbfb8aa3b, v129
	v_mul_f32_e32 v136, 0xbfb8aa3b, v136
	v_mul_f32_e32 v126, 0xbfb8aa3b, v126
	v_mul_f32_e32 v137, 0xbfb8aa3b, v137
	v_mul_f32_e32 v127, 0xbfb8aa3b, v127
	v_mul_f32_e32 v169, 0xbfb8aa3b, v169
	v_mul_f32_e32 v128, 0xbfb8aa3b, v128
	v_mul_f32_e32 v176, 0xbfb8aa3b, v176
	v_exp_f32_e32 v129, v129
	v_exp_f32_e32 v136, v136
	v_exp_f32_e32 v126, v126
	v_exp_f32_e32 v137, v137
	v_exp_f32_e32 v127, v127
	v_exp_f32_e32 v169, v169
	v_exp_f32_e32 v128, v128
	v_exp_f32_e32 v176, v176
	v_add_f32_e32 v129, 1.0, v129
	v_add_f32_e32 v136, 1.0, v136
	v_add_f32_e32 v126, 1.0, v126
	v_add_f32_e32 v137, 1.0, v137
	v_add_f32_e32 v127, 1.0, v127
	v_add_f32_e32 v169, 1.0, v169
	v_add_f32_e32 v128, 1.0, v128
	v_add_f32_e32 v176, 1.0, v176
	v_rcp_f32_e32 v129, v129
	v_rcp_f32_e32 v136, v136
	v_rcp_f32_e32 v126, v126
	v_rcp_f32_e32 v137, v137
	v_rcp_f32_e32 v127, v127
	v_rcp_f32_e32 v169, v169
	v_rcp_f32_e32 v128, v128
	v_rcp_f32_e32 v176, v176
	v_mul_f32_e32 v109, v109, v129
	v_mul_f32_e32 v110, v110, v136
	v_mul_f32_e32 v111, v111, v126
	v_mul_f32_e32 v112, v112, v137
	v_mul_f32_e32 v113, v113, v127
	v_mul_f32_e32 v126, v106, v169
	v_mul_f32_e32 v127, v107, v128
	v_mul_f32_e32 v128, v108, v176
	v_cvt_pk_bf16_f32 v106, v110, v111
	v_cvt_pk_bf16_f32 v107, v112, v113
	v_cvt_pk_bf16_f32 v108, v126, v127
	v_cvt_pk_bf16_f32 v109, v128, v109
	global_store_dwordx4 v[122:123], v[106:109], off
	s_nop 0
	v_add_u32_e32 v126, 0x80, v168
	v_lshlrev_b64 v[106:107], 11, v[134:135]
	v_ashrrev_i32_e32 v127, 31, v126
	v_lshl_add_u64 v[106:107], s[10:11], 0, v[106:107]
	v_lshlrev_b64 v[108:109], 10, v[126:127]
	v_lshl_add_u64 v[106:107], v[106:107], 0, v[166:167]
	v_lshl_add_u64 v[108:109], v[170:171], 0, v[108:109]
	s_waitcnt vmcnt(13)
; __device__ __forceinline__ unsigned cvt_pk_bf16(float lo, float hi) { unsigned r; asm volatile("v_cvt_pk_bf16_f32 %0, %1, %2" : "=v"(r) : "v"(lo), "v"(hi)); return r; }
; __device__ __forceinline__ float bflo(unsigned u) { return __uint_as_float(u << 16); }
; __device__ __forceinline__ float bfhi(unsigned u) { return __uint_as_float(u & 0xffff0000u); }
; __device__ __forceinline__ float sigm(float v) { return __builtin_amdgcn_rcpf(1.0f + __expf(-v)); }
; DI float bflo(unsigned u) { return __uint_as_float(u << 16); }
; DI float bfhi(unsigned u) { return __uint_as_float(u & 0xffff0000u); }
;     __device__ __forceinline__ void operator()(const f32x4 (&acc)[2][2][4][2], const Unit& u, int wr, int wc, int fr, int fq) const {
;     ...
;         for (int bj = 0; bj < 2; ++bj) {
;             const f32x4 b0 = *(const f32x4*)(gb + col0 + bj * HALF), b1 = *(const f32x4*)(gb + col0 + bj * HALF + 4);
; #pragma unroll
;             for (int ai = 0; ai < 2; ++ai)
; #pragma unroll
;                 for (int m = 0; m < 4; ++m) { const size_t row = (size_t)(row0 + ai * HALF + m * 16);
;                     const u32x4 g = *(const u32x4*)(gbase + row * 512 + gcol0 + bj * HALF);
;                     const f32x4 v0 = acc[ai][bj][m][0], v1 = acc[ai][bj][m][1];
;                     float r0 = v0[0] * sigm(bflo(g.x) + b0[0]), r1 = v0[1] * sigm(bfhi(g.x) + b0[1]), r2 = v0[2] * sigm(bflo(g.y) + b0[2]), r3 = v0[3] * sigm(bfhi(g.y) + b0[3]);
;                     float r4 = v1[0] * sigm(bflo(g.z) + b1[0]), r5 = v1[1] * sigm(bfhi(g.z) + b1[1]), r6 = v1[2] * sigm(bflo(g.w) + b1[2]), r7 = v1[3] * sigm(bfhi(g.w) + b1[3]);
;                     bf16_t* op = Mo + row * 1024 + col0 + bj * HALF;
;                     if (accum) { const u32x4 p = *(const u32x4*)op; r0 += bflo(p.x); r1 += bfhi(p.x); r2 += bflo(p.y); r3 += bfhi(p.y); r4 += bflo(p.z); r5 += bfhi(p.z); r6 += bflo(p.w); r7 += bfhi(p.w); }
;                     u32x4 w; w.x = cvt_pk_bf16(r0, r1); w.y = cvt_pk_bf16(r2, r3); w.z = cvt_pk_bf16(r4, r5); w.w = cvt_pk_bf16(r6, r7);
;                     *(u32x4*)op = w; }
	v_lshlrev_b32_e32 v135, 16, v215
	v_and_b32_e32 v113, 0xffff0000, v215
	v_lshlrev_b32_e32 v128, 16, v212
	v_and_b32_e32 v110, 0xffff0000, v212
	v_lshlrev_b32_e32 v129, 16, v213
	v_and_b32_e32 v111, 0xffff0000, v213
	v_lshlrev_b32_e32 v134, 16, v214
	v_and_b32_e32 v112, 0xffff0000, v214
	s_mov_b64 s[98:99], 0x20000
	v_lshl_add_u64 v[248:249], v[250:251], 0, s[98:99]
	global_load_dwordx4 v[212:215], v[248:249], off offset:256
	v_add_f32_e32 v113, v117, v113
	v_add_f32_e32 v128, v118, v128
	v_add_f32_e32 v110, v119, v110
	v_add_f32_e32 v129, v120, v129
	v_add_f32_e32 v111, v121, v111
	v_add_f32_e32 v134, v114, v134
	v_add_f32_e32 v112, v115, v112
	v_add_f32_e32 v135, v116, v135
	v_mul_f32_e32 v113, 0xbfb8aa3b, v113
	v_mul_f32_e32 v128, 0xbfb8aa3b, v128
	v_mul_f32_e32 v110, 0xbfb8aa3b, v110
	v_mul_f32_e32 v129, 0xbfb8aa3b, v129
	v_mul_f32_e32 v111, 0xbfb8aa3b, v111
	v_mul_f32_e32 v134, 0xbfb8aa3b, v134
	v_mul_f32_e32 v112, 0xbfb8aa3b, v112
	v_mul_f32_e32 v135, 0xbfb8aa3b, v135
	v_exp_f32_e32 v113, v113
	v_exp_f32_e32 v128, v128
	v_exp_f32_e32 v110, v110
	v_exp_f32_e32 v129, v129
	v_exp_f32_e32 v111, v111
	v_exp_f32_e32 v134, v134
	v_exp_f32_e32 v112, v112
	v_exp_f32_e32 v135, v135
	v_add_f32_e32 v113, 1.0, v113
	v_add_f32_e32 v128, 1.0, v128
	v_add_f32_e32 v110, 1.0, v110
	v_add_f32_e32 v129, 1.0, v129
	v_add_f32_e32 v111, 1.0, v111
	v_add_f32_e32 v134, 1.0, v134
	v_add_f32_e32 v112, 1.0, v112
	v_add_f32_e32 v135, 1.0, v135
	v_rcp_f32_e32 v113, v113
	v_rcp_f32_e32 v128, v128
	v_rcp_f32_e32 v110, v110
	v_rcp_f32_e32 v129, v129
	v_rcp_f32_e32 v111, v111
	v_rcp_f32_e32 v134, v134
	v_rcp_f32_e32 v112, v112
	v_rcp_f32_e32 v135, v135
	v_mul_f32_e32 v101, v101, v113
	v_mul_f32_e32 v102, v102, v128
	v_mul_f32_e32 v103, v103, v110
	v_mul_f32_e32 v104, v104, v129
	v_mul_f32_e32 v105, v105, v111
	v_mul_f32_e32 v110, v98, v134
	v_mul_f32_e32 v111, v99, v112
	v_mul_f32_e32 v112, v100, v135
	v_cvt_pk_bf16_f32 v98, v102, v103
	v_cvt_pk_bf16_f32 v99, v104, v105
	v_cvt_pk_bf16_f32 v100, v110, v111
	v_cvt_pk_bf16_f32 v101, v112, v101
	global_store_dwordx4 v[106:107], v[98:101], off
	s_nop 0
	v_add_u32_e32 v110, 0x90, v168
	v_lshlrev_b64 v[98:99], 11, v[126:127]
	v_ashrrev_i32_e32 v111, 31, v110
	v_lshl_add_u64 v[98:99], s[10:11], 0, v[98:99]
	v_lshlrev_b64 v[100:101], 10, v[110:111]
	v_lshl_add_u64 v[98:99], v[98:99], 0, v[166:167]
	v_lshl_add_u64 v[100:101], v[170:171], 0, v[100:101]
	s_waitcnt vmcnt(14)
	v_lshlrev_b32_e32 v127, 16, v219
	v_and_b32_e32 v105, 0xffff0000, v219
	v_lshlrev_b32_e32 v112, 16, v216
	v_and_b32_e32 v102, 0xffff0000, v216
	v_lshlrev_b32_e32 v113, 16, v217
	v_and_b32_e32 v103, 0xffff0000, v217
	v_lshlrev_b32_e32 v126, 16, v218
	v_and_b32_e32 v104, 0xffff0000, v218
	s_mov_b64 s[98:99], 0x24000
	v_lshl_add_u64 v[248:249], v[250:251], 0, s[98:99]
	global_load_dwordx4 v[216:219], v[248:249], off offset:256
	v_add_f32_e32 v105, v117, v105
	v_add_f32_e32 v112, v118, v112
	v_add_f32_e32 v102, v119, v102
	v_add_f32_e32 v113, v120, v113
	v_add_f32_e32 v103, v121, v103
	v_add_f32_e32 v126, v114, v126
	v_add_f32_e32 v104, v115, v104
	v_add_f32_e32 v127, v116, v127
	v_mul_f32_e32 v105, 0xbfb8aa3b, v105
	v_mul_f32_e32 v112, 0xbfb8aa3b, v112
	v_mul_f32_e32 v102, 0xbfb8aa3b, v102
	v_mul_f32_e32 v113, 0xbfb8aa3b, v113
	v_mul_f32_e32 v103, 0xbfb8aa3b, v103
	v_mul_f32_e32 v126, 0xbfb8aa3b, v126
	v_mul_f32_e32 v104, 0xbfb8aa3b, v104
	v_mul_f32_e32 v127, 0xbfb8aa3b, v127
	v_exp_f32_e32 v105, v105
	v_exp_f32_e32 v112, v112
	v_exp_f32_e32 v102, v102
	v_exp_f32_e32 v113, v113
	v_exp_f32_e32 v103, v103
	v_exp_f32_e32 v126, v126
	v_exp_f32_e32 v104, v104
	v_exp_f32_e32 v127, v127
	v_add_f32_e32 v105, 1.0, v105
	v_add_f32_e32 v112, 1.0, v112
	v_add_f32_e32 v102, 1.0, v102
	v_add_f32_e32 v113, 1.0, v113
	v_add_f32_e32 v103, 1.0, v103
	v_add_f32_e32 v126, 1.0, v126
	v_add_f32_e32 v104, 1.0, v104
	v_add_f32_e32 v127, 1.0, v127
	v_rcp_f32_e32 v105, v105
	v_rcp_f32_e32 v112, v112
	v_rcp_f32_e32 v102, v102
	v_rcp_f32_e32 v113, v113
	v_rcp_f32_e32 v103, v103
	v_rcp_f32_e32 v126, v126
	v_rcp_f32_e32 v104, v104
	v_rcp_f32_e32 v127, v127
	v_mul_f32_e32 v93, v93, v105
	v_mul_f32_e32 v94, v94, v112
	v_mul_f32_e32 v95, v95, v102
	v_mul_f32_e32 v96, v96, v113
	v_mul_f32_e32 v97, v97, v103
	v_mul_f32_e32 v102, v90, v126
	v_mul_f32_e32 v103, v91, v104
	v_mul_f32_e32 v104, v92, v127
	v_cvt_pk_bf16_f32 v90, v94, v95
	v_cvt_pk_bf16_f32 v91, v96, v97
	v_cvt_pk_bf16_f32 v92, v102, v103
	v_cvt_pk_bf16_f32 v93, v104, v93
	global_store_dwordx4 v[98:99], v[90:93], off
	s_nop 0
	v_add_u32_e32 v102, 0xa0, v168
	v_lshlrev_b64 v[90:91], 11, v[110:111]
	v_ashrrev_i32_e32 v103, 31, v102
	v_lshl_add_u64 v[90:91], s[10:11], 0, v[90:91]
	v_lshlrev_b64 v[92:93], 10, v[102:103]
	v_lshl_add_u64 v[90:91], v[90:91], 0, v[166:167]
	v_lshl_add_u64 v[92:93], v[170:171], 0, v[92:93]
	s_waitcnt vmcnt(15)
; __device__ __forceinline__ unsigned cvt_pk_bf16(float lo, float hi) { unsigned r; asm volatile("v_cvt_pk_bf16_f32 %0, %1, %2" : "=v"(r) : "v"(lo), "v"(hi)); return r; }
; __device__ __forceinline__ float bflo(unsigned u) { return __uint_as_float(u << 16); }
; __device__ __forceinline__ float bfhi(unsigned u) { return __uint_as_float(u & 0xffff0000u); }
; __device__ __forceinline__ float sigm(float v) { return __builtin_amdgcn_rcpf(1.0f + __expf(-v)); }
; DI float bflo(unsigned u) { return __uint_as_float(u << 16); }
; DI float bfhi(unsigned u) { return __uint_as_float(u & 0xffff0000u); }
;     __device__ __forceinline__ void operator()(const f32x4 (&acc)[2][2][4][2], const Unit& u, int wr, int wc, int fr, int fq) const {
;     ...
;         for (int bj = 0; bj < 2; ++bj) {
;             const f32x4 b0 = *(const f32x4*)(gb + col0 + bj * HALF), b1 = *(const f32x4*)(gb + col0 + bj * HALF + 4);
; #pragma unroll
;             for (int ai = 0; ai < 2; ++ai)
; #pragma unroll
;                 for (int m = 0; m < 4; ++m) { const size_t row = (size_t)(row0 + ai * HALF + m * 16);
;                     const u32x4 g = *(const u32x4*)(gbase + row * 512 + gcol0 + bj * HALF);
;                     const f32x4 v0 = acc[ai][bj][m][0], v1 = acc[ai][bj][m][1];
;                     float r0 = v0[0] * sigm(bflo(g.x) + b0[0]), r1 = v0[1] * sigm(bfhi(g.x) + b0[1]), r2 = v0[2] * sigm(bflo(g.y) + b0[2]), r3 = v0[3] * sigm(bfhi(g.y) + b0[3]);
;                     float r4 = v1[0] * sigm(bflo(g.z) + b1[0]), r5 = v1[1] * sigm(bfhi(g.z) + b1[1]), r6 = v1[2] * sigm(bflo(g.w) + b1[2]), r7 = v1[3] * sigm(bfhi(g.w) + b1[3]);
;                     bf16_t* op = Mo + row * 1024 + col0 + bj * HALF;
;                     if (accum) { const u32x4 p = *(const u32x4*)op; r0 += bflo(p.x); r1 += bfhi(p.x); r2 += bflo(p.y); r3 += bfhi(p.y); r4 += bflo(p.z); r5 += bfhi(p.z); r6 += bflo(p.w); r7 += bfhi(p.w); }
;                     u32x4 w; w.x = cvt_pk_bf16(r0, r1); w.y = cvt_pk_bf16(r2, r3); w.z = cvt_pk_bf16(r4, r5); w.w = cvt_pk_bf16(r6, r7);
;                     *(u32x4*)op = w; }
	v_lshlrev_b32_e32 v111, 16, v223
	v_and_b32_e32 v97, 0xffff0000, v223
	v_lshlrev_b32_e32 v104, 16, v220
	v_and_b32_e32 v94, 0xffff0000, v220
	v_lshlrev_b32_e32 v105, 16, v221
	v_and_b32_e32 v95, 0xffff0000, v221
	v_lshlrev_b32_e32 v110, 16, v222
	v_and_b32_e32 v96, 0xffff0000, v222
	s_mov_b64 s[98:99], 0x28000
	v_lshl_add_u64 v[248:249], v[250:251], 0, s[98:99]
	global_load_dwordx4 v[220:223], v[248:249], off offset:256
	v_add_f32_e32 v97, v117, v97
	v_add_f32_e32 v104, v118, v104
	v_add_f32_e32 v94, v119, v94
	v_add_f32_e32 v105, v120, v105
	v_add_f32_e32 v95, v121, v95
	v_add_f32_e32 v110, v114, v110
	v_add_f32_e32 v96, v115, v96
	v_add_f32_e32 v111, v116, v111
	v_mul_f32_e32 v97, 0xbfb8aa3b, v97
	v_mul_f32_e32 v104, 0xbfb8aa3b, v104
	v_mul_f32_e32 v94, 0xbfb8aa3b, v94
	v_mul_f32_e32 v105, 0xbfb8aa3b, v105
	v_mul_f32_e32 v95, 0xbfb8aa3b, v95
	v_mul_f32_e32 v110, 0xbfb8aa3b, v110
	v_mul_f32_e32 v96, 0xbfb8aa3b, v96
	v_mul_f32_e32 v111, 0xbfb8aa3b, v111
	v_exp_f32_e32 v97, v97
	v_exp_f32_e32 v104, v104
	v_exp_f32_e32 v94, v94
	v_exp_f32_e32 v105, v105
	v_exp_f32_e32 v95, v95
	v_exp_f32_e32 v110, v110
	v_exp_f32_e32 v96, v96
	v_exp_f32_e32 v111, v111
	v_add_f32_e32 v97, 1.0, v97
	v_add_f32_e32 v104, 1.0, v104
	v_add_f32_e32 v94, 1.0, v94
	v_add_f32_e32 v105, 1.0, v105
	v_add_f32_e32 v95, 1.0, v95
	v_add_f32_e32 v110, 1.0, v110
	v_add_f32_e32 v96, 1.0, v96
	v_add_f32_e32 v111, 1.0, v111
	v_rcp_f32_e32 v97, v97
	v_rcp_f32_e32 v104, v104
	v_rcp_f32_e32 v94, v94
	v_rcp_f32_e32 v105, v105
	v_rcp_f32_e32 v95, v95
	v_rcp_f32_e32 v110, v110
	v_rcp_f32_e32 v96, v96
	v_rcp_f32_e32 v111, v111
	v_mul_f32_e32 v85, v85, v97
	v_mul_f32_e32 v86, v86, v104
	v_mul_f32_e32 v87, v87, v94
	v_mul_f32_e32 v88, v88, v105
	v_mul_f32_e32 v89, v89, v95
	v_mul_f32_e32 v94, v82, v110
	v_mul_f32_e32 v95, v83, v96
	v_mul_f32_e32 v96, v84, v111
	v_cvt_pk_bf16_f32 v82, v86, v87
	v_cvt_pk_bf16_f32 v83, v88, v89
	v_cvt_pk_bf16_f32 v84, v94, v95
	v_cvt_pk_bf16_f32 v85, v96, v85
	global_store_dwordx4 v[90:91], v[82:85], off
	s_nop 0
	v_add_u32_e32 v94, 0xb0, v168
	v_lshlrev_b64 v[82:83], 11, v[102:103]
	v_ashrrev_i32_e32 v95, 31, v94
	v_lshl_add_u64 v[82:83], s[10:11], 0, v[82:83]
	v_lshlrev_b64 v[84:85], 10, v[94:95]
	v_lshl_add_u64 v[82:83], v[82:83], 0, v[166:167]
	v_lshl_add_u64 v[84:85], v[170:171], 0, v[84:85]
	s_waitcnt vmcnt(16)
	v_lshlrev_b32_e32 v103, 16, v227
	v_and_b32_e32 v89, 0xffff0000, v227
	v_lshlrev_b32_e32 v96, 16, v224
	v_and_b32_e32 v86, 0xffff0000, v224
	v_lshlrev_b32_e32 v97, 16, v225
	v_and_b32_e32 v87, 0xffff0000, v225
	v_lshlrev_b32_e32 v102, 16, v226
	v_and_b32_e32 v88, 0xffff0000, v226
	s_mov_b64 s[98:99], 0x2c000
	v_lshl_add_u64 v[248:249], v[250:251], 0, s[98:99]
	global_load_dwordx4 v[224:227], v[248:249], off offset:256
	v_add_f32_e32 v89, v117, v89
	v_add_f32_e32 v96, v118, v96
	v_add_f32_e32 v86, v119, v86
	v_add_f32_e32 v97, v120, v97
	v_add_f32_e32 v87, v121, v87
	v_add_f32_e32 v102, v114, v102
	v_add_f32_e32 v88, v115, v88
	v_add_f32_e32 v103, v116, v103
	v_mul_f32_e32 v89, 0xbfb8aa3b, v89
	v_mul_f32_e32 v96, 0xbfb8aa3b, v96
	v_mul_f32_e32 v86, 0xbfb8aa3b, v86
	v_mul_f32_e32 v97, 0xbfb8aa3b, v97
	v_mul_f32_e32 v87, 0xbfb8aa3b, v87
	v_mul_f32_e32 v102, 0xbfb8aa3b, v102
	v_mul_f32_e32 v88, 0xbfb8aa3b, v88
	v_mul_f32_e32 v103, 0xbfb8aa3b, v103
	v_exp_f32_e32 v89, v89
	v_exp_f32_e32 v96, v96
	v_exp_f32_e32 v86, v86
	v_exp_f32_e32 v97, v97
	v_exp_f32_e32 v87, v87
	v_exp_f32_e32 v102, v102
	v_exp_f32_e32 v88, v88
	v_exp_f32_e32 v103, v103
	v_add_f32_e32 v89, 1.0, v89
	v_add_f32_e32 v96, 1.0, v96
	v_add_f32_e32 v86, 1.0, v86
	v_add_f32_e32 v97, 1.0, v97
	v_add_f32_e32 v87, 1.0, v87
	v_add_f32_e32 v102, 1.0, v102
	v_add_f32_e32 v88, 1.0, v88
	v_add_f32_e32 v103, 1.0, v103
	v_rcp_f32_e32 v89, v89
	v_rcp_f32_e32 v96, v96
	v_rcp_f32_e32 v86, v86
	v_rcp_f32_e32 v97, v97
	v_rcp_f32_e32 v87, v87
	v_rcp_f32_e32 v102, v102
	v_rcp_f32_e32 v88, v88
	v_rcp_f32_e32 v103, v103
	v_mul_f32_e32 v77, v77, v89
	v_mul_f32_e32 v78, v78, v96
	v_mul_f32_e32 v79, v79, v86
	v_mul_f32_e32 v80, v80, v97
	v_mul_f32_e32 v81, v81, v87
	v_mul_f32_e32 v86, v74, v102
	v_mul_f32_e32 v87, v75, v88
	v_mul_f32_e32 v88, v76, v103
	v_cvt_pk_bf16_f32 v74, v78, v79
	v_cvt_pk_bf16_f32 v75, v80, v81
	v_cvt_pk_bf16_f32 v76, v86, v87
	v_cvt_pk_bf16_f32 v77, v88, v77
	global_store_dwordx4 v[82:83], v[74:77], off
	s_nop 0
	s_waitcnt vmcnt(17)
	v_lshlrev_b32_e32 v87, 16, v191
	v_and_b32_e32 v79, 0xffff0000, v191
	v_lshlrev_b32_e32 v80, 16, v188
	v_and_b32_e32 v76, 0xffff0000, v188
	v_lshlrev_b32_e32 v81, 16, v189
	v_and_b32_e32 v77, 0xffff0000, v189
	v_lshlrev_b32_e32 v86, 16, v190
	v_and_b32_e32 v78, 0xffff0000, v190
	v_add_f32_e32 v79, v117, v79
	v_add_f32_e32 v80, v118, v80
	v_add_f32_e32 v76, v119, v76
	v_add_f32_e32 v81, v120, v81
	v_add_f32_e32 v77, v121, v77
	v_add_f32_e32 v86, v114, v86
	v_add_f32_e32 v78, v115, v78
	v_add_f32_e32 v87, v116, v87
	v_mul_f32_e32 v79, 0xbfb8aa3b, v79
	v_mul_f32_e32 v80, 0xbfb8aa3b, v80
	v_mul_f32_e32 v76, 0xbfb8aa3b, v76
	v_mul_f32_e32 v81, 0xbfb8aa3b, v81
	v_mul_f32_e32 v77, 0xbfb8aa3b, v77
	v_mul_f32_e32 v86, 0xbfb8aa3b, v86
	v_mul_f32_e32 v78, 0xbfb8aa3b, v78
	v_mul_f32_e32 v87, 0xbfb8aa3b, v87
	v_exp_f32_e32 v79, v79
	v_exp_f32_e32 v80, v80
	v_exp_f32_e32 v76, v76
	v_exp_f32_e32 v81, v81
	v_exp_f32_e32 v77, v77
	v_exp_f32_e32 v86, v86
	v_exp_f32_e32 v78, v78
	v_exp_f32_e32 v87, v87
	v_add_f32_e32 v79, 1.0, v79
	v_add_f32_e32 v80, 1.0, v80
	v_add_f32_e32 v76, 1.0, v76
	v_add_f32_e32 v81, 1.0, v81
	v_add_f32_e32 v77, 1.0, v77
	v_add_f32_e32 v86, 1.0, v86
	v_add_f32_e32 v78, 1.0, v78
	v_add_f32_e32 v87, 1.0, v87
	v_rcp_f32_e32 v79, v79
	v_rcp_f32_e32 v80, v80
	v_rcp_f32_e32 v76, v76
	v_rcp_f32_e32 v81, v81
	v_rcp_f32_e32 v77, v77
	v_rcp_f32_e32 v86, v86
	v_rcp_f32_e32 v78, v78
	v_rcp_f32_e32 v87, v87
	v_lshlrev_b64 v[74:75], 11, v[94:95]
	v_lshl_add_u64 v[74:75], s[10:11], 0, v[74:75]
	v_lshl_add_u64 v[74:75], v[74:75], 0, v[166:167]
	v_mul_f32_e32 v69, v69, v79
	v_mul_f32_e32 v70, v70, v80
	v_mul_f32_e32 v71, v71, v76
	v_mul_f32_e32 v72, v72, v81
	v_mul_f32_e32 v73, v73, v77
	v_mul_f32_e32 v76, v66, v86
	v_mul_f32_e32 v77, v67, v78
	v_mul_f32_e32 v78, v68, v87
	v_cvt_pk_bf16_f32 v66, v70, v71
	v_cvt_pk_bf16_f32 v67, v72, v73
	v_cvt_pk_bf16_f32 v68, v76, v77
	v_cvt_pk_bf16_f32 v69, v78, v69
	global_store_dwordx4 v[74:75], v[66:69], off
	s_nop 0
	v_mov_b32_e32 v70, v240
	v_mov_b32_e32 v71, v241
	v_mov_b32_e32 v72, v242
	v_mov_b32_e32 v73, v243
	s_nop 0
	v_mov_b32_e32 v66, v244
	v_mov_b32_e32 v67, v245
	v_mov_b32_e32 v68, v246
	v_mov_b32_e32 v69, v247
	s_waitcnt vmcnt(14)
; __device__ __forceinline__ unsigned cvt_pk_bf16(float lo, float hi) { unsigned r; asm volatile("v_cvt_pk_bf16_f32 %0, %1, %2" : "=v"(r) : "v"(lo), "v"(hi)); return r; }
; __device__ __forceinline__ float bflo(unsigned u) { return __uint_as_float(u << 16); }
; __device__ __forceinline__ float bfhi(unsigned u) { return __uint_as_float(u & 0xffff0000u); }
; __device__ __forceinline__ float sigm(float v) { return __builtin_amdgcn_rcpf(1.0f + __expf(-v)); }
; DI float bflo(unsigned u) { return __uint_as_float(u << 16); }
; DI float bfhi(unsigned u) { return __uint_as_float(u & 0xffff0000u); }
;     __device__ __forceinline__ void operator()(const f32x4 (&acc)[2][2][4][2], const Unit& u, int wr, int wc, int fr, int fq) const {
;     ...
;         for (int bj = 0; bj < 2; ++bj) {
;             const f32x4 b0 = *(const f32x4*)(gb + col0 + bj * HALF), b1 = *(const f32x4*)(gb + col0 + bj * HALF + 4);
; #pragma unroll
;             for (int ai = 0; ai < 2; ++ai)
; #pragma unroll
;                 for (int m = 0; m < 4; ++m) { const size_t row = (size_t)(row0 + ai * HALF + m * 16);
;                     const u32x4 g = *(const u32x4*)(gbase + row * 512 + gcol0 + bj * HALF);
;                     const f32x4 v0 = acc[ai][bj][m][0], v1 = acc[ai][bj][m][1];
;                     float r0 = v0[0] * sigm(bflo(g.x) + b0[0]), r1 = v0[1] * sigm(bfhi(g.x) + b0[1]), r2 = v0[2] * sigm(bflo(g.y) + b0[2]), r3 = v0[3] * sigm(bfhi(g.y) + b0[3]);
;                     float r4 = v1[0] * sigm(bflo(g.z) + b1[0]), r5 = v1[1] * sigm(bfhi(g.z) + b1[1]), r6 = v1[2] * sigm(bflo(g.w) + b1[2]), r7 = v1[3] * sigm(bfhi(g.w) + b1[3]);
;                     bf16_t* op = Mo + row * 1024 + col0 + bj * HALF;
;                     if (accum) { const u32x4 p = *(const u32x4*)op; r0 += bflo(p.x); r1 += bfhi(p.x); r2 += bflo(p.y); r3 += bfhi(p.y); r4 += bflo(p.z); r5 += bfhi(p.z); r6 += bflo(p.w); r7 += bfhi(p.w); }
;                     u32x4 w; w.x = cvt_pk_bf16(r0, r1); w.y = cvt_pk_bf16(r2, r3); w.z = cvt_pk_bf16(r4, r5); w.w = cvt_pk_bf16(r6, r7);
;                     *(u32x4*)op = w; }
	v_lshlrev_b32_e32 v87, 16, v195
	v_and_b32_e32 v79, 0xffff0000, v195
	v_lshlrev_b32_e32 v80, 16, v192
	v_and_b32_e32 v76, 0xffff0000, v192
	v_lshlrev_b32_e32 v81, 16, v193
	v_and_b32_e32 v77, 0xffff0000, v193
	v_lshlrev_b32_e32 v86, 16, v194
	v_and_b32_e32 v78, 0xffff0000, v194
	s_nop 0
	v_add_f32_e32 v79, v69, v79
	v_add_f32_e32 v80, v70, v80
	v_add_f32_e32 v76, v71, v76
	v_add_f32_e32 v81, v72, v81
	v_add_f32_e32 v77, v73, v77
	v_add_f32_e32 v86, v66, v86
	v_add_f32_e32 v78, v67, v78
	v_add_f32_e32 v87, v68, v87
	v_mul_f32_e32 v79, 0xbfb8aa3b, v79
	v_mul_f32_e32 v80, 0xbfb8aa3b, v80
	v_mul_f32_e32 v76, 0xbfb8aa3b, v76
	v_mul_f32_e32 v81, 0xbfb8aa3b, v81
	v_mul_f32_e32 v77, 0xbfb8aa3b, v77
	v_mul_f32_e32 v86, 0xbfb8aa3b, v86
	v_mul_f32_e32 v78, 0xbfb8aa3b, v78
	v_mul_f32_e32 v87, 0xbfb8aa3b, v87
	v_exp_f32_e32 v79, v79
	v_exp_f32_e32 v80, v80
	v_exp_f32_e32 v76, v76
	v_exp_f32_e32 v81, v81
	v_exp_f32_e32 v77, v77
	v_exp_f32_e32 v86, v86
	v_exp_f32_e32 v78, v78
	v_exp_f32_e32 v87, v87
	v_add_f32_e32 v79, 1.0, v79
	v_add_f32_e32 v80, 1.0, v80
	v_add_f32_e32 v76, 1.0, v76
	v_add_f32_e32 v81, 1.0, v81
	v_add_f32_e32 v77, 1.0, v77
	v_add_f32_e32 v86, 1.0, v86
	v_add_f32_e32 v78, 1.0, v78
	v_add_f32_e32 v87, 1.0, v87
	v_rcp_f32_e32 v79, v79
	v_rcp_f32_e32 v80, v80
	v_rcp_f32_e32 v76, v76
	v_rcp_f32_e32 v81, v81
	v_rcp_f32_e32 v77, v77
	v_rcp_f32_e32 v86, v86
	v_rcp_f32_e32 v78, v78
	v_rcp_f32_e32 v87, v87
	v_mul_f32_e32 v61, v61, v79
	v_mul_f32_e32 v62, v62, v80
	v_mul_f32_e32 v63, v63, v76
	v_mul_f32_e32 v64, v64, v81
	v_mul_f32_e32 v65, v65, v77
	v_mul_f32_e32 v76, v58, v86
	v_mul_f32_e32 v77, v59, v78
	v_mul_f32_e32 v78, v60, v87
	v_cvt_pk_bf16_f32 v58, v62, v63
	v_cvt_pk_bf16_f32 v59, v64, v65
	v_cvt_pk_bf16_f32 v60, v76, v77
	v_cvt_pk_bf16_f32 v61, v78, v61
	global_store_dwordx4 v[154:155], v[58:61], off offset:256
	s_nop 0
	s_waitcnt vmcnt(17)
	v_lshlrev_b32_e32 v65, 16, v255
	v_and_b32_e32 v61, 0xffff0000, v255
	v_lshlrev_b32_e32 v62, 16, v252
	v_and_b32_e32 v58, 0xffff0000, v252
	v_lshlrev_b32_e32 v63, 16, v253
	v_and_b32_e32 v59, 0xffff0000, v253
	v_lshlrev_b32_e32 v64, 16, v254
	v_and_b32_e32 v60, 0xffff0000, v254
	v_add_f32_e32 v61, v69, v61
	v_add_f32_e32 v62, v70, v62
	v_add_f32_e32 v58, v71, v58
	v_add_f32_e32 v63, v72, v63
	v_add_f32_e32 v59, v73, v59
	v_add_f32_e32 v64, v66, v64
	v_add_f32_e32 v60, v67, v60
	v_add_f32_e32 v65, v68, v65
	v_mul_f32_e32 v61, 0xbfb8aa3b, v61
	v_mul_f32_e32 v62, 0xbfb8aa3b, v62
	v_mul_f32_e32 v58, 0xbfb8aa3b, v58
	v_mul_f32_e32 v63, 0xbfb8aa3b, v63
	v_mul_f32_e32 v59, 0xbfb8aa3b, v59
	v_mul_f32_e32 v64, 0xbfb8aa3b, v64
	v_mul_f32_e32 v60, 0xbfb8aa3b, v60
	v_mul_f32_e32 v65, 0xbfb8aa3b, v65
	v_exp_f32_e32 v61, v61
	v_exp_f32_e32 v62, v62
	v_exp_f32_e32 v58, v58
	v_exp_f32_e32 v63, v63
	v_exp_f32_e32 v59, v59
	v_exp_f32_e32 v64, v64
	v_exp_f32_e32 v60, v60
	v_exp_f32_e32 v65, v65
	v_add_f32_e32 v61, 1.0, v61
	v_add_f32_e32 v62, 1.0, v62
	v_add_f32_e32 v58, 1.0, v58
	v_add_f32_e32 v63, 1.0, v63
	v_add_f32_e32 v59, 1.0, v59
	v_add_f32_e32 v64, 1.0, v64
	v_add_f32_e32 v60, 1.0, v60
	v_add_f32_e32 v65, 1.0, v65
	v_rcp_f32_e32 v61, v61
	v_rcp_f32_e32 v62, v62
	v_rcp_f32_e32 v58, v58
	v_rcp_f32_e32 v63, v63
	v_rcp_f32_e32 v59, v59
	v_rcp_f32_e32 v64, v64
	v_rcp_f32_e32 v60, v60
	v_rcp_f32_e32 v65, v65
	v_mul_f32_e32 v53, v53, v61
	v_mul_f32_e32 v54, v54, v62
	v_mul_f32_e32 v55, v55, v58
	v_mul_f32_e32 v56, v56, v63
	v_mul_f32_e32 v57, v57, v59
	v_mul_f32_e32 v58, v50, v64
	v_mul_f32_e32 v59, v51, v60
	v_mul_f32_e32 v60, v52, v65
	v_cvt_pk_bf16_f32 v50, v54, v55
	v_cvt_pk_bf16_f32 v51, v56, v57
	v_cvt_pk_bf16_f32 v52, v58, v59
	v_cvt_pk_bf16_f32 v53, v60, v53
	global_store_dwordx4 v[130:131], v[50:53], off offset:256
	s_nop 0
	s_waitcnt vmcnt(14)
	v_lshlrev_b32_e32 v57, 16, v207
	v_and_b32_e32 v53, 0xffff0000, v207
	v_lshlrev_b32_e32 v54, 16, v204
	v_and_b32_e32 v50, 0xffff0000, v204
	v_lshlrev_b32_e32 v55, 16, v205
	v_and_b32_e32 v51, 0xffff0000, v205
	v_lshlrev_b32_e32 v56, 16, v206
	v_and_b32_e32 v52, 0xffff0000, v206
	v_add_f32_e32 v53, v69, v53
	v_add_f32_e32 v54, v70, v54
	v_add_f32_e32 v50, v71, v50
	v_add_f32_e32 v55, v72, v55
	v_add_f32_e32 v51, v73, v51
	v_add_f32_e32 v56, v66, v56
	v_add_f32_e32 v52, v67, v52
	v_add_f32_e32 v57, v68, v57
	v_mul_f32_e32 v53, 0xbfb8aa3b, v53
	v_mul_f32_e32 v54, 0xbfb8aa3b, v54
	v_mul_f32_e32 v50, 0xbfb8aa3b, v50
	v_mul_f32_e32 v55, 0xbfb8aa3b, v55
	v_mul_f32_e32 v51, 0xbfb8aa3b, v51
	v_mul_f32_e32 v56, 0xbfb8aa3b, v56
	v_mul_f32_e32 v52, 0xbfb8aa3b, v52
	v_mul_f32_e32 v57, 0xbfb8aa3b, v57
	v_exp_f32_e32 v53, v53
	v_exp_f32_e32 v54, v54
	v_exp_f32_e32 v50, v50
	v_exp_f32_e32 v55, v55
	v_exp_f32_e32 v51, v51
	v_exp_f32_e32 v56, v56
	v_exp_f32_e32 v52, v52
	v_exp_f32_e32 v57, v57
	v_add_f32_e32 v53, 1.0, v53
	v_add_f32_e32 v54, 1.0, v54
	v_add_f32_e32 v50, 1.0, v50
	v_add_f32_e32 v55, 1.0, v55
	v_add_f32_e32 v51, 1.0, v51
	v_add_f32_e32 v56, 1.0, v56
	v_add_f32_e32 v52, 1.0, v52
	v_add_f32_e32 v57, 1.0, v57
	v_rcp_f32_e32 v53, v53
	v_rcp_f32_e32 v54, v54
	v_rcp_f32_e32 v50, v50
	v_rcp_f32_e32 v55, v55
	v_rcp_f32_e32 v51, v51
	v_rcp_f32_e32 v56, v56
	v_rcp_f32_e32 v52, v52
	v_rcp_f32_e32 v57, v57
	v_mul_f32_e32 v45, v45, v53
	v_mul_f32_e32 v46, v46, v54
	v_mul_f32_e32 v47, v47, v50
	v_mul_f32_e32 v48, v48, v55
	v_mul_f32_e32 v49, v49, v51
	v_mul_f32_e32 v50, v42, v56
	v_mul_f32_e32 v51, v43, v52
	v_mul_f32_e32 v52, v44, v57
	v_cvt_pk_bf16_f32 v42, v46, v47
	v_cvt_pk_bf16_f32 v43, v48, v49
	v_cvt_pk_bf16_f32 v44, v50, v51
	v_cvt_pk_bf16_f32 v45, v52, v45
	global_store_dwordx4 v[122:123], v[42:45], off offset:256
	s_nop 0
	s_waitcnt vmcnt(13)
; __device__ __forceinline__ unsigned cvt_pk_bf16(float lo, float hi) { unsigned r; asm volatile("v_cvt_pk_bf16_f32 %0, %1, %2" : "=v"(r) : "v"(lo), "v"(hi)); return r; }
; __device__ __forceinline__ float bflo(unsigned u) { return __uint_as_float(u << 16); }
; __device__ __forceinline__ float bfhi(unsigned u) { return __uint_as_float(u & 0xffff0000u); }
; __device__ __forceinline__ float sigm(float v) { return __builtin_amdgcn_rcpf(1.0f + __expf(-v)); }
; DI float bflo(unsigned u) { return __uint_as_float(u << 16); }
; DI float bfhi(unsigned u) { return __uint_as_float(u & 0xffff0000u); }
;     __device__ __forceinline__ void operator()(const f32x4 (&acc)[2][2][4][2], const Unit& u, int wr, int wc, int fr, int fq) const {
;     ...
;         for (int bj = 0; bj < 2; ++bj) {
;             const f32x4 b0 = *(const f32x4*)(gb + col0 + bj * HALF), b1 = *(const f32x4*)(gb + col0 + bj * HALF + 4);
; #pragma unroll
;             for (int ai = 0; ai < 2; ++ai)
; #pragma unroll
;                 for (int m = 0; m < 4; ++m) { const size_t row = (size_t)(row0 + ai * HALF + m * 16);
;                     const u32x4 g = *(const u32x4*)(gbase + row * 512 + gcol0 + bj * HALF);
;                     const f32x4 v0 = acc[ai][bj][m][0], v1 = acc[ai][bj][m][1];
;                     float r0 = v0[0] * sigm(bflo(g.x) + b0[0]), r1 = v0[1] * sigm(bfhi(g.x) + b0[1]), r2 = v0[2] * sigm(bflo(g.y) + b0[2]), r3 = v0[3] * sigm(bfhi(g.y) + b0[3]);
;                     float r4 = v1[0] * sigm(bflo(g.z) + b1[0]), r5 = v1[1] * sigm(bfhi(g.z) + b1[1]), r6 = v1[2] * sigm(bflo(g.w) + b1[2]), r7 = v1[3] * sigm(bfhi(g.w) + b1[3]);
;                     bf16_t* op = Mo + row * 1024 + col0 + bj * HALF;
;                     if (accum) { const u32x4 p = *(const u32x4*)op; r0 += bflo(p.x); r1 += bfhi(p.x); r2 += bflo(p.y); r3 += bfhi(p.y); r4 += bflo(p.z); r5 += bfhi(p.z); r6 += bflo(p.w); r7 += bfhi(p.w); }
;                     u32x4 w; w.x = cvt_pk_bf16(r0, r1); w.y = cvt_pk_bf16(r2, r3); w.z = cvt_pk_bf16(r4, r5); w.w = cvt_pk_bf16(r6, r7);
;                     *(u32x4*)op = w; }
	v_lshlrev_b32_e32 v49, 16, v211
	v_and_b32_e32 v45, 0xffff0000, v211
	v_lshlrev_b32_e32 v46, 16, v208
	v_and_b32_e32 v42, 0xffff0000, v208
	v_lshlrev_b32_e32 v47, 16, v209
	v_and_b32_e32 v43, 0xffff0000, v209
	v_lshlrev_b32_e32 v48, 16, v210
	v_and_b32_e32 v44, 0xffff0000, v210
	v_add_f32_e32 v45, v69, v45
	v_add_f32_e32 v46, v70, v46
	v_add_f32_e32 v42, v71, v42
	v_add_f32_e32 v47, v72, v47
	v_add_f32_e32 v43, v73, v43
	v_add_f32_e32 v48, v66, v48
	v_add_f32_e32 v44, v67, v44
	v_add_f32_e32 v49, v68, v49
	v_mul_f32_e32 v45, 0xbfb8aa3b, v45
	v_mul_f32_e32 v46, 0xbfb8aa3b, v46
	v_mul_f32_e32 v42, 0xbfb8aa3b, v42
	v_mul_f32_e32 v47, 0xbfb8aa3b, v47
	v_mul_f32_e32 v43, 0xbfb8aa3b, v43
	v_mul_f32_e32 v48, 0xbfb8aa3b, v48
	v_mul_f32_e32 v44, 0xbfb8aa3b, v44
	v_mul_f32_e32 v49, 0xbfb8aa3b, v49
	v_exp_f32_e32 v45, v45
	v_exp_f32_e32 v46, v46
	v_exp_f32_e32 v42, v42
	v_exp_f32_e32 v47, v47
	v_exp_f32_e32 v43, v43
	v_exp_f32_e32 v48, v48
	v_exp_f32_e32 v44, v44
	v_exp_f32_e32 v49, v49
	v_add_f32_e32 v45, 1.0, v45
	v_add_f32_e32 v46, 1.0, v46
	v_add_f32_e32 v42, 1.0, v42
	v_add_f32_e32 v47, 1.0, v47
	v_add_f32_e32 v43, 1.0, v43
	v_add_f32_e32 v48, 1.0, v48
	v_add_f32_e32 v44, 1.0, v44
	v_add_f32_e32 v49, 1.0, v49
	v_rcp_f32_e32 v45, v45
	v_rcp_f32_e32 v46, v46
	v_rcp_f32_e32 v42, v42
	v_rcp_f32_e32 v47, v47
	v_rcp_f32_e32 v43, v43
	v_rcp_f32_e32 v48, v48
	v_rcp_f32_e32 v44, v44
	v_rcp_f32_e32 v49, v49
	v_mul_f32_e32 v37, v37, v45
	v_mul_f32_e32 v38, v38, v46
	v_mul_f32_e32 v39, v39, v42
	v_mul_f32_e32 v40, v40, v47
	v_mul_f32_e32 v41, v41, v43
	v_mul_f32_e32 v42, v34, v48
	v_mul_f32_e32 v43, v35, v44
	v_mul_f32_e32 v44, v36, v49
	v_cvt_pk_bf16_f32 v34, v38, v39
	v_cvt_pk_bf16_f32 v35, v40, v41
	v_cvt_pk_bf16_f32 v36, v42, v43
	v_cvt_pk_bf16_f32 v37, v44, v37
	global_store_dwordx4 v[106:107], v[34:37], off offset:256
	s_nop 0
	s_waitcnt vmcnt(12)
	v_lshlrev_b32_e32 v41, 16, v215
	v_and_b32_e32 v37, 0xffff0000, v215
	v_lshlrev_b32_e32 v38, 16, v212
	v_and_b32_e32 v34, 0xffff0000, v212
	v_lshlrev_b32_e32 v39, 16, v213
	v_and_b32_e32 v35, 0xffff0000, v213
	v_lshlrev_b32_e32 v40, 16, v214
	v_and_b32_e32 v36, 0xffff0000, v214
	v_add_f32_e32 v37, v69, v37
	v_add_f32_e32 v38, v70, v38
	v_add_f32_e32 v34, v71, v34
	v_add_f32_e32 v39, v72, v39
	v_add_f32_e32 v35, v73, v35
	v_add_f32_e32 v40, v66, v40
	v_add_f32_e32 v36, v67, v36
	v_add_f32_e32 v41, v68, v41
	v_mul_f32_e32 v37, 0xbfb8aa3b, v37
	v_mul_f32_e32 v38, 0xbfb8aa3b, v38
	v_mul_f32_e32 v34, 0xbfb8aa3b, v34
	v_mul_f32_e32 v39, 0xbfb8aa3b, v39
	v_mul_f32_e32 v35, 0xbfb8aa3b, v35
	v_mul_f32_e32 v40, 0xbfb8aa3b, v40
	v_mul_f32_e32 v36, 0xbfb8aa3b, v36
	v_mul_f32_e32 v41, 0xbfb8aa3b, v41
	v_exp_f32_e32 v37, v37
	v_exp_f32_e32 v38, v38
	v_exp_f32_e32 v34, v34
	v_exp_f32_e32 v39, v39
	v_exp_f32_e32 v35, v35
	v_exp_f32_e32 v40, v40
	v_exp_f32_e32 v36, v36
	v_exp_f32_e32 v41, v41
	v_add_f32_e32 v37, 1.0, v37
	v_add_f32_e32 v38, 1.0, v38
	v_add_f32_e32 v34, 1.0, v34
	v_add_f32_e32 v39, 1.0, v39
	v_add_f32_e32 v35, 1.0, v35
	v_add_f32_e32 v40, 1.0, v40
	v_add_f32_e32 v36, 1.0, v36
	v_add_f32_e32 v41, 1.0, v41
	v_rcp_f32_e32 v37, v37
	v_rcp_f32_e32 v38, v38
	v_rcp_f32_e32 v34, v34
	v_rcp_f32_e32 v39, v39
	v_rcp_f32_e32 v35, v35
	v_rcp_f32_e32 v40, v40
	v_rcp_f32_e32 v36, v36
	v_rcp_f32_e32 v41, v41
	v_mul_f32_e32 v29, v29, v37
	v_mul_f32_e32 v30, v30, v38
	v_mul_f32_e32 v31, v31, v34
	v_mul_f32_e32 v32, v32, v39
	v_mul_f32_e32 v33, v33, v35
	v_mul_f32_e32 v34, v26, v40
	v_mul_f32_e32 v35, v27, v36
	v_mul_f32_e32 v36, v28, v41
	v_cvt_pk_bf16_f32 v26, v30, v31
	v_cvt_pk_bf16_f32 v27, v32, v33
	v_cvt_pk_bf16_f32 v28, v34, v35
	v_cvt_pk_bf16_f32 v29, v36, v29
	global_store_dwordx4 v[98:99], v[26:29], off offset:256
	s_nop 0
	s_waitcnt vmcnt(11)
	v_lshlrev_b32_e32 v33, 16, v219
	v_and_b32_e32 v29, 0xffff0000, v219
	v_lshlrev_b32_e32 v30, 16, v216
	v_and_b32_e32 v26, 0xffff0000, v216
	v_lshlrev_b32_e32 v31, 16, v217
	v_and_b32_e32 v27, 0xffff0000, v217
	v_lshlrev_b32_e32 v32, 16, v218
	v_and_b32_e32 v28, 0xffff0000, v218
	v_add_f32_e32 v29, v69, v29
	v_add_f32_e32 v30, v70, v30
	v_add_f32_e32 v26, v71, v26
	v_add_f32_e32 v31, v72, v31
	v_add_f32_e32 v27, v73, v27
	v_add_f32_e32 v32, v66, v32
	v_add_f32_e32 v28, v67, v28
	v_add_f32_e32 v33, v68, v33
	v_mul_f32_e32 v29, 0xbfb8aa3b, v29
	v_mul_f32_e32 v30, 0xbfb8aa3b, v30
	v_mul_f32_e32 v26, 0xbfb8aa3b, v26
	v_mul_f32_e32 v31, 0xbfb8aa3b, v31
	v_mul_f32_e32 v27, 0xbfb8aa3b, v27
	v_mul_f32_e32 v32, 0xbfb8aa3b, v32
	v_mul_f32_e32 v28, 0xbfb8aa3b, v28
	v_mul_f32_e32 v33, 0xbfb8aa3b, v33
	v_exp_f32_e32 v29, v29
	v_exp_f32_e32 v30, v30
	v_exp_f32_e32 v26, v26
	v_exp_f32_e32 v31, v31
	v_exp_f32_e32 v27, v27
	v_exp_f32_e32 v32, v32
	v_exp_f32_e32 v28, v28
	v_exp_f32_e32 v33, v33
	v_add_f32_e32 v29, 1.0, v29
	v_add_f32_e32 v30, 1.0, v30
	v_add_f32_e32 v26, 1.0, v26
	v_add_f32_e32 v31, 1.0, v31
	v_add_f32_e32 v27, 1.0, v27
	v_add_f32_e32 v32, 1.0, v32
	v_add_f32_e32 v28, 1.0, v28
	v_add_f32_e32 v33, 1.0, v33
	v_rcp_f32_e32 v29, v29
	v_rcp_f32_e32 v30, v30
	v_rcp_f32_e32 v26, v26
	v_rcp_f32_e32 v31, v31
	v_rcp_f32_e32 v27, v27
	v_rcp_f32_e32 v32, v32
	v_rcp_f32_e32 v28, v28
	v_rcp_f32_e32 v33, v33
	v_mul_f32_e32 v21, v21, v29
	v_mul_f32_e32 v22, v22, v30
	v_mul_f32_e32 v23, v23, v26
	v_mul_f32_e32 v24, v24, v31
	v_mul_f32_e32 v25, v25, v27
	v_mul_f32_e32 v26, v18, v32
	v_mul_f32_e32 v27, v19, v28
	v_mul_f32_e32 v28, v20, v33
	v_cvt_pk_bf16_f32 v18, v22, v23
	v_cvt_pk_bf16_f32 v19, v24, v25
	v_cvt_pk_bf16_f32 v20, v26, v27
	v_cvt_pk_bf16_f32 v21, v28, v21
	global_store_dwordx4 v[90:91], v[18:21], off offset:256
	s_nop 0
	s_waitcnt vmcnt(10)
; __device__ __forceinline__ unsigned cvt_pk_bf16(float lo, float hi) { unsigned r; asm volatile("v_cvt_pk_bf16_f32 %0, %1, %2" : "=v"(r) : "v"(lo), "v"(hi)); return r; }
; __device__ __forceinline__ float bflo(unsigned u) { return __uint_as_float(u << 16); }
; __device__ __forceinline__ float bfhi(unsigned u) { return __uint_as_float(u & 0xffff0000u); }
; __device__ __forceinline__ float sigm(float v) { return __builtin_amdgcn_rcpf(1.0f + __expf(-v)); }
; DI float bflo(unsigned u) { return __uint_as_float(u << 16); }
; DI float bfhi(unsigned u) { return __uint_as_float(u & 0xffff0000u); }
;     __device__ __forceinline__ void operator()(const f32x4 (&acc)[2][2][4][2], const Unit& u, int wr, int wc, int fr, int fq) const {
;     ...
;         for (int bj = 0; bj < 2; ++bj) {
;             const f32x4 b0 = *(const f32x4*)(gb + col0 + bj * HALF), b1 = *(const f32x4*)(gb + col0 + bj * HALF + 4);
; #pragma unroll
;             for (int ai = 0; ai < 2; ++ai)
; #pragma unroll
;                 for (int m = 0; m < 4; ++m) { const size_t row = (size_t)(row0 + ai * HALF + m * 16);
;                     const u32x4 g = *(const u32x4*)(gbase + row * 512 + gcol0 + bj * HALF);
;                     const f32x4 v0 = acc[ai][bj][m][0], v1 = acc[ai][bj][m][1];
;                     float r0 = v0[0] * sigm(bflo(g.x) + b0[0]), r1 = v0[1] * sigm(bfhi(g.x) + b0[1]), r2 = v0[2] * sigm(bflo(g.y) + b0[2]), r3 = v0[3] * sigm(bfhi(g.y) + b0[3]);
;                     float r4 = v1[0] * sigm(bflo(g.z) + b1[0]), r5 = v1[1] * sigm(bfhi(g.z) + b1[1]), r6 = v1[2] * sigm(bflo(g.w) + b1[2]), r7 = v1[3] * sigm(bfhi(g.w) + b1[3]);
;                     bf16_t* op = Mo + row * 1024 + col0 + bj * HALF;
;                     if (accum) { const u32x4 p = *(const u32x4*)op; r0 += bflo(p.x); r1 += bfhi(p.x); r2 += bflo(p.y); r3 += bfhi(p.y); r4 += bflo(p.z); r5 += bfhi(p.z); r6 += bflo(p.w); r7 += bfhi(p.w); }
;                     u32x4 w; w.x = cvt_pk_bf16(r0, r1); w.y = cvt_pk_bf16(r2, r3); w.z = cvt_pk_bf16(r4, r5); w.w = cvt_pk_bf16(r6, r7);
;                     *(u32x4*)op = w; }
	v_lshlrev_b32_e32 v25, 16, v223
	v_and_b32_e32 v21, 0xffff0000, v223
	v_lshlrev_b32_e32 v22, 16, v220
	v_and_b32_e32 v18, 0xffff0000, v220
	v_lshlrev_b32_e32 v23, 16, v221
	v_and_b32_e32 v19, 0xffff0000, v221
	v_lshlrev_b32_e32 v24, 16, v222
	v_and_b32_e32 v20, 0xffff0000, v222
	v_add_f32_e32 v21, v69, v21
	v_add_f32_e32 v22, v70, v22
	v_add_f32_e32 v18, v71, v18
	v_add_f32_e32 v23, v72, v23
	v_add_f32_e32 v19, v73, v19
	v_add_f32_e32 v24, v66, v24
	v_add_f32_e32 v20, v67, v20
	v_add_f32_e32 v25, v68, v25
	v_mul_f32_e32 v21, 0xbfb8aa3b, v21
	v_mul_f32_e32 v22, 0xbfb8aa3b, v22
	v_mul_f32_e32 v18, 0xbfb8aa3b, v18
	v_mul_f32_e32 v23, 0xbfb8aa3b, v23
	v_mul_f32_e32 v19, 0xbfb8aa3b, v19
	v_mul_f32_e32 v24, 0xbfb8aa3b, v24
	v_mul_f32_e32 v20, 0xbfb8aa3b, v20
	v_mul_f32_e32 v25, 0xbfb8aa3b, v25
	v_exp_f32_e32 v21, v21
	v_exp_f32_e32 v22, v22
	v_exp_f32_e32 v18, v18
	v_exp_f32_e32 v23, v23
	v_exp_f32_e32 v19, v19
	v_exp_f32_e32 v24, v24
	v_exp_f32_e32 v20, v20
	v_exp_f32_e32 v25, v25
	v_add_f32_e32 v21, 1.0, v21
	v_add_f32_e32 v22, 1.0, v22
	v_add_f32_e32 v18, 1.0, v18
	v_add_f32_e32 v23, 1.0, v23
	v_add_f32_e32 v19, 1.0, v19
	v_add_f32_e32 v24, 1.0, v24
	v_add_f32_e32 v20, 1.0, v20
	v_add_f32_e32 v25, 1.0, v25
	v_rcp_f32_e32 v21, v21
	v_rcp_f32_e32 v22, v22
	v_rcp_f32_e32 v18, v18
	v_rcp_f32_e32 v23, v23
	v_rcp_f32_e32 v19, v19
	v_rcp_f32_e32 v24, v24
	v_rcp_f32_e32 v20, v20
	v_rcp_f32_e32 v25, v25
	v_mul_f32_e32 v13, v13, v21
	v_mul_f32_e32 v14, v14, v22
	v_mul_f32_e32 v15, v15, v18
	v_mul_f32_e32 v16, v16, v23
	v_mul_f32_e32 v17, v17, v19
	v_mul_f32_e32 v18, v10, v24
	v_mul_f32_e32 v19, v11, v20
	v_mul_f32_e32 v20, v12, v25
	v_cvt_pk_bf16_f32 v10, v14, v15
	v_cvt_pk_bf16_f32 v11, v16, v17
	v_cvt_pk_bf16_f32 v12, v18, v19
	v_cvt_pk_bf16_f32 v13, v20, v13
	global_store_dwordx4 v[82:83], v[10:13], off offset:256
	s_nop 0
	s_waitcnt vmcnt(9)
	v_lshlrev_b32_e32 v17, 16, v227
	v_and_b32_e32 v13, 0xffff0000, v227
	v_lshlrev_b32_e32 v14, 16, v224
	v_and_b32_e32 v10, 0xffff0000, v224
	v_lshlrev_b32_e32 v15, 16, v225
	v_and_b32_e32 v11, 0xffff0000, v225
	v_lshlrev_b32_e32 v16, 16, v226
	v_and_b32_e32 v12, 0xffff0000, v226
	v_add_f32_e32 v13, v69, v13
	v_add_f32_e32 v14, v70, v14
	v_add_f32_e32 v10, v71, v10
	v_add_f32_e32 v15, v72, v15
	v_add_f32_e32 v11, v73, v11
	v_add_f32_e32 v16, v66, v16
	v_add_f32_e32 v12, v67, v12
	v_add_f32_e32 v17, v68, v17
	v_mul_f32_e32 v13, 0xbfb8aa3b, v13
	v_mul_f32_e32 v14, 0xbfb8aa3b, v14
	v_mul_f32_e32 v10, 0xbfb8aa3b, v10
	v_mul_f32_e32 v15, 0xbfb8aa3b, v15
	v_mul_f32_e32 v11, 0xbfb8aa3b, v11
	v_mul_f32_e32 v16, 0xbfb8aa3b, v16
	v_mul_f32_e32 v12, 0xbfb8aa3b, v12
	v_mul_f32_e32 v17, 0xbfb8aa3b, v17
	v_exp_f32_e32 v13, v13
	v_exp_f32_e32 v14, v14
	v_exp_f32_e32 v10, v10
	v_exp_f32_e32 v15, v15
	v_exp_f32_e32 v11, v11
	v_exp_f32_e32 v16, v16
	v_exp_f32_e32 v12, v12
	v_exp_f32_e32 v17, v17
	v_add_f32_e32 v13, 1.0, v13
	v_add_f32_e32 v14, 1.0, v14
	v_add_f32_e32 v10, 1.0, v10
	v_add_f32_e32 v15, 1.0, v15
	v_add_f32_e32 v11, 1.0, v11
	v_add_f32_e32 v16, 1.0, v16
	v_add_f32_e32 v12, 1.0, v12
	v_add_f32_e32 v17, 1.0, v17
	v_rcp_f32_e32 v13, v13
	v_rcp_f32_e32 v14, v14
	v_rcp_f32_e32 v10, v10
	v_rcp_f32_e32 v15, v15
	v_rcp_f32_e32 v11, v11
	v_rcp_f32_e32 v16, v16
	v_rcp_f32_e32 v12, v12
	v_rcp_f32_e32 v17, v17
	v_mul_f32_e32 v5, v5, v13
	v_mul_f32_e32 v6, v6, v14
	v_mul_f32_e32 v7, v7, v10
	v_mul_f32_e32 v8, v8, v15
	v_mul_f32_e32 v9, v9, v11
	v_mul_f32_e32 v10, v2, v16
	v_mul_f32_e32 v11, v3, v12
	v_mul_f32_e32 v12, v4, v17
	v_cvt_pk_bf16_f32 v2, v6, v7
	v_cvt_pk_bf16_f32 v3, v8, v9
	v_cvt_pk_bf16_f32 v4, v10, v11
	v_cvt_pk_bf16_f32 v5, v12, v5
	global_store_dwordx4 v[74:75], v[2:5], off offset:256
	s_cbranch_vccnz .LBB0_869
	s_andn2_b64 vcc, exec, s[0:1]
	s_cbranch_vccnz .LBB0_868
	s_barrier
	s_branch .LBB0_868
